# ml_out conv weights: all six weight tiles loaded up front (spare VGPRs) instead of five serial load-wait round trips
# speedup vs baseline: 1.0103x; 1.0103x over previous
; #define LAS __attribute__((address_space(3)))
; DEV bf16x8 pack8(const float* x) { u32x4 o; o.x = pk2(x[0], x[1]); o.y = pk2(x[2], x[3]); o.z = pk2(x[4], x[5]); o.w = pk2(x[6], x[7]); return __builtin_bit_cast(bf16x8, o); }
; DEV void ml_out_item(const Fr& F, int l, int it, MoPre& P, int nx) {
;     ...
;     for (int i = 0; i < 2; ++i) { const int idx = tid + NTHR * i; const int s = idx >> 3, c8 = (idx & 7) * 8;
;         *(LAS u32x4*)(Vs + s * 72 + c8) = P.v[i];
;         *(LAS u32x4*)(Ks + s * 72 + c8) = P.k[i];
;         const float* cw = F.in[I_CONVW] + l * 1536 + h * 64 + c8;
;         f32x2 a[4]; float x[8];
; #pragma unroll
;         for (int q = 0; q < 4; ++q) a[q] = (f32x2){0.f, 0.f};
; #pragma unroll
;         for (int tap = 0; tap < 3; ++tap) { unpack8(P.q[i][tap], x); const f32x4 w0 = *(const f32x4*)(cw + tap * 512), w1 = *(const f32x4*)(cw + tap * 512 + 4);
;             a[0] += (f32x2){x[0], x[1]} * (f32x2){w0[0], w0[1]}; a[1] += (f32x2){x[2], x[3]} * (f32x2){w0[2], w0[3]};
;             a[2] += (f32x2){x[4], x[5]} * (f32x2){w1[0], w1[1]}; a[3] += (f32x2){x[6], x[7]} * (f32x2){w1[2], w1[3]}; }
;         float k[8];
; #pragma unroll
;         for (int q = 0; q < 4; ++q) { const f32x2 r = fsilu2(a[q]); k[2 * q] = r.x; k[2 * q + 1] = r.y; }
;         *(LAS bf16x8*)(Qs + s * 72 + c8) = pack8(k); }
.LBB0_789:
	s_waitcnt vmcnt(15)
	ds_write_b128 v132, v[4:7] offset:36864
	s_waitcnt vmcnt(14)
	ds_write_b128 v132, v[8:11] offset:18432
	v_lshl_add_u64 v[2:3], v[130:131], 0, s[60:61]
	global_load_dwordx4 v[96:99], v[2:3], off
	global_load_dwordx4 v[92:95], v[2:3], off offset:16
	global_load_dwordx4 v[244:247], v[2:3], off offset:2048
	global_load_dwordx4 v[248:251], v[2:3], off offset:2064
	s_mov_b64 s[4:5], 0x1000
	v_lshl_add_u64 v[112:113], v[2:3], 0, s[4:5]
	global_load_dwordx4 v[252:255], v[112:113], off
	global_load_dwordx4 v[116:119], v[112:113], off offset:16
	v_lshlrev_b32_e32 v80, 16, v14
	v_and_b32_e32 v81, 0xffff0000, v14
	v_lshlrev_b32_e32 v82, 16, v15
	v_and_b32_e32 v83, 0xffff0000, v15
	v_lshlrev_b32_e32 v76, 16, v12
	v_and_b32_e32 v77, 0xffff0000, v12
	v_lshlrev_b32_e32 v78, 16, v13
	v_and_b32_e32 v79, 0xffff0000, v13
	v_lshlrev_b32_e32 v88, 16, v16
	v_and_b32_e32 v89, 0xffff0000, v16
	v_lshlrev_b32_e32 v90, 16, v17
	v_and_b32_e32 v91, 0xffff0000, v17
	s_movk_i32 s4, 0x1000
	v_lshlrev_b32_e32 v100, 16, v18
	v_and_b32_e32 v101, 0xffff0000, v18
	v_lshlrev_b32_e32 v102, 16, v19
	v_and_b32_e32 v103, 0xffff0000, v19
	v_lshlrev_b32_e32 v104, 16, v20
	v_and_b32_e32 v105, 0xffff0000, v20
	v_lshlrev_b32_e32 v106, 16, v21
	v_and_b32_e32 v107, 0xffff0000, v21
	v_lshlrev_b32_e32 v108, 16, v22
	v_and_b32_e32 v109, 0xffff0000, v22
	v_lshlrev_b32_e32 v110, 16, v23
	v_and_b32_e32 v111, 0xffff0000, v23
	s_waitcnt vmcnt(5)
	v_pk_fma_f32 v[76:77], v[96:97], v[76:77], 0 op_sel_hi:[1,1,0]
	s_waitcnt vmcnt(4)
	v_pk_fma_f32 v[84:85], v[92:93], v[80:81], 0 op_sel_hi:[1,1,0]
	v_pk_fma_f32 v[86:87], v[94:95], v[82:83], 0 op_sel_hi:[1,1,0]
	v_pk_fma_f32 v[78:79], v[98:99], v[78:79], 0 op_sel_hi:[1,1,0]
	s_waitcnt vmcnt(3)
	v_mov_b32_e32 v80, v244
	v_mov_b32_e32 v81, v245
	v_mov_b32_e32 v82, v246
	v_mov_b32_e32 v83, v247
	v_pk_fma_f32 v[88:89], v[80:81], v[88:89], v[76:77]
	v_pk_fma_f32 v[90:91], v[82:83], v[90:91], v[78:79]
	v_add_co_u32_e32 v2, vcc, s4, v2
	s_mov_b32 s4, 0xbfb8aa3b
	s_nop 0
	v_addc_co_u32_e32 v3, vcc, 0, v3, vcc
	s_waitcnt vmcnt(2)
	v_mov_b32_e32 v76, v248
	v_mov_b32_e32 v77, v249
	v_mov_b32_e32 v78, v250
	v_mov_b32_e32 v79, v251
	v_pk_fma_f32 v[100:101], v[76:77], v[100:101], v[84:85]
	v_pk_fma_f32 v[102:103], v[78:79], v[102:103], v[86:87]
	s_waitcnt vmcnt(1)
	v_mov_b32_e32 v84, v252
	v_mov_b32_e32 v85, v253
	v_mov_b32_e32 v86, v254
	v_mov_b32_e32 v87, v255
	v_pk_fma_f32 v[2:3], v[84:85], v[104:105], v[88:89]
	v_pk_fma_f32 v[104:105], v[86:87], v[106:107], v[90:91]
	v_pk_mul_f32 v[106:107], v[2:3], s[4:5] op_sel_hi:[1,0]
	s_waitcnt vmcnt(0)
	v_mov_b32_e32 v88, v116
	v_mov_b32_e32 v89, v117
	v_mov_b32_e32 v90, v118
	v_mov_b32_e32 v91, v119
	v_pk_fma_f32 v[100:101], v[88:89], v[108:109], v[100:101]
	v_exp_f32_e32 v106, v106
	v_exp_f32_e32 v107, v107
	v_pk_fma_f32 v[102:103], v[90:91], v[110:111], v[102:103]
	v_pk_add_f32 v[106:107], v[106:107], 1.0 op_sel_hi:[1,0]
	s_nop 0
	v_rcp_f32_e32 v106, v106
	v_rcp_f32_e32 v107, v107
	s_nop 0
	v_pk_mul_f32 v[2:3], v[2:3], v[106:107]
	v_pk_mul_f32 v[106:107], v[104:105], s[4:5] op_sel_hi:[1,0]
	s_nop 0
	v_exp_f32_e32 v106, v106
	v_exp_f32_e32 v107, v107
	s_nop 0
	v_pk_add_f32 v[106:107], v[106:107], 1.0 op_sel_hi:[1,0]
	s_nop 0
	v_rcp_f32_e32 v106, v106
	v_rcp_f32_e32 v107, v107
	s_nop 0
	v_pk_mul_f32 v[104:105], v[104:105], v[106:107]
	v_pk_mul_f32 v[106:107], v[100:101], s[4:5] op_sel_hi:[1,0]
	s_nop 0
	v_exp_f32_e32 v106, v106
	v_exp_f32_e32 v107, v107
	s_nop 0
	v_pk_add_f32 v[106:107], v[106:107], 1.0 op_sel_hi:[1,0]
	s_nop 0
	v_rcp_f32_e32 v106, v106
	v_rcp_f32_e32 v107, v107
	s_nop 0
	v_pk_mul_f32 v[106:107], v[100:101], v[106:107]
	v_pk_mul_f32 v[100:101], v[102:103], s[4:5] op_sel_hi:[1,0]
	s_nop 0
	v_exp_f32_e32 v100, v100
	v_exp_f32_e32 v101, v101
	s_nop 0
	v_pk_add_f32 v[100:101], v[100:101], 1.0 op_sel_hi:[1,0]
	s_nop 0
	v_rcp_f32_e32 v100, v100
	v_rcp_f32_e32 v101, v101
	s_nop 0
	v_pk_mul_f32 v[108:109], v[102:103], v[100:101]
	v_cvt_pk_bf16_f32 v100, v2, v3
	v_cvt_pk_bf16_f32 v101, v104, v105
	v_cvt_pk_bf16_f32 v102, v106, v107
	s_nop 0
	v_cvt_pk_bf16_f32 v103, v108, v109
	ds_write_b128 v132, v[100:103]
	ds_write_b128 v134, v[24:27] offset:36864
	ds_write_b128 v134, v[28:31] offset:18432
	v_lshlrev_b32_e32 v2, 16, v32
	v_and_b32_e32 v3, 0xffff0000, v32
	v_lshlrev_b32_e32 v100, 16, v33
	v_and_b32_e32 v101, 0xffff0000, v33
	v_pk_fma_f32 v[2:3], v[96:97], v[2:3], 0 op_sel_hi:[1,1,0]
	v_pk_fma_f32 v[96:97], v[98:99], v[100:101], 0 op_sel_hi:[1,1,0]
	v_lshlrev_b32_e32 v98, 16, v36
	v_and_b32_e32 v99, 0xffff0000, v36
	v_lshlrev_b32_e32 v100, 16, v37
	v_and_b32_e32 v101, 0xffff0000, v37
	v_pk_fma_f32 v[2:3], v[80:81], v[98:99], v[2:3]
	v_pk_fma_f32 v[80:81], v[82:83], v[100:101], v[96:97]
	v_lshlrev_b32_e32 v82, 16, v40
	v_and_b32_e32 v83, 0xffff0000, v40
	v_pk_fma_f32 v[2:3], v[84:85], v[82:83], v[2:3]
	v_lshlrev_b32_e32 v102, 16, v34
	v_pk_mul_f32 v[82:83], v[2:3], s[4:5] op_sel_hi:[1,0]
	v_and_b32_e32 v103, 0xffff0000, v34
	v_exp_f32_e32 v82, v82
	v_exp_f32_e32 v83, v83
	v_pk_fma_f32 v[92:93], v[92:93], v[102:103], 0 op_sel_hi:[1,1,0]
	v_lshlrev_b32_e32 v102, 16, v38
	v_and_b32_e32 v103, 0xffff0000, v38
; #define LAS __attribute__((address_space(3)))
; DEV unsigned pk2(float lo, float hi) { unsigned r; asm("v_cvt_pk_bf16_f32 %0, %1, %2" : "=v"(r) : "v"(lo), "v"(hi)); return r; }
; DEV bf16x8 pack8(const float* x) { u32x4 o; o.x = pk2(x[0], x[1]); o.y = pk2(x[2], x[3]); o.z = pk2(x[4], x[5]); o.w = pk2(x[6], x[7]); return __builtin_bit_cast(bf16x8, o); }
; DEV GateRaw ml_gates_load(const Fr& F, int l, int row0, int h, int dir, int lane) {
;     const int u0 = 2 * lane, u1 = u0 + 1; const int s0 = dir ? 127 - u0 : u0, s1 = dir ? 127 - u1 : u1;
;     const float bi = F.in[I_GATEB][l * 16 + (dir * 2) * 4 + h], bf = F.in[I_GATEB][l * 16 + (dir * 2 + 1) * 4 + h];
;     const bf16_t* z0 = F.Z + (size_t)(row0 + s0) * ZS + ZC_MG, * z1 = F.Z + (size_t)(row0 + s1) * ZS + ZC_MG;
;     GateRaw r; r.li0 = bf2f(z0[(dir * 2) * 4 + h]) + bi; r.li1 = bf2f(z1[(dir * 2) * 4 + h]) + bi;
;     r.lp0 = bf2f(z0[(dir * 2 + 1) * 4 + h]) + bf; r.lp1 = bf2f(z1[(dir * 2 + 1) * 4 + h]) + bf; return r;
; DEV void ml_out_item(const Fr& F, int l, int it, MoPre& P, int nx) {
;     ...
;         for (int tap = 0; tap < 3; ++tap) { unpack8(P.q[i][tap], x); const f32x4 w0 = *(const f32x4*)(cw + tap * 512), w1 = *(const f32x4*)(cw + tap * 512 + 4);
;             a[0] += (f32x2){x[0], x[1]} * (f32x2){w0[0], w0[1]}; a[1] += (f32x2){x[2], x[3]} * (f32x2){w0[2], w0[3]};
;             a[2] += (f32x2){x[4], x[5]} * (f32x2){w1[0], w1[1]}; a[3] += (f32x2){x[6], x[7]} * (f32x2){w1[2], w1[3]}; }
;         float k[8];
; #pragma unroll
;         for (int q = 0; q < 4; ++q) { const f32x2 r = fsilu2(a[q]); k[2 * q] = r.x; k[2 * q + 1] = r.y; }
;         *(LAS bf16x8*)(Qs + s * 72 + c8) = pack8(k); }
; #pragma unroll
;     for (int i = 0; i < 4; ++i) { const int idx = tid + NTHR * i; const int dir = idx >> 10, e = (idx >> 4) & 63, d4 = (idx & 15) * 4;
;         u32x2 o; o.x = pk2(P.ct[i][0], P.ct[i][1]); o.y = pk2(P.ct[i][2], P.ct[i][3]); *(LAS u32x2*)(CT + (dir * 64 + e) * 72 + d4) = o; }
;     if (tid < 128) nv[tid] = P.nvv;
;     __syncthreads();
;     if (nx >= 0) ml_out_prefetch(F, l, nx, P);
	v_pk_add_f32 v[82:83], v[82:83], 1.0 op_sel_hi:[1,0]
	v_pk_fma_f32 v[76:77], v[76:77], v[102:103], v[92:93]
	v_rcp_f32_e32 v82, v82
	v_rcp_f32_e32 v83, v83
	v_lshlrev_b32_e32 v92, 16, v41
	v_and_b32_e32 v93, 0xffff0000, v41
	v_pk_fma_f32 v[80:81], v[86:87], v[92:93], v[80:81]
	v_pk_mul_f32 v[2:3], v[2:3], v[82:83]
	v_pk_mul_f32 v[82:83], v[80:81], s[4:5] op_sel_hi:[1,0]
	v_lshlrev_b32_e32 v104, 16, v35
	v_exp_f32_e32 v82, v82
	v_exp_f32_e32 v83, v83
	v_and_b32_e32 v105, 0xffff0000, v35
	v_pk_fma_f32 v[94:95], v[94:95], v[104:105], 0 op_sel_hi:[1,1,0]
	v_lshlrev_b32_e32 v104, 16, v39
	v_pk_add_f32 v[82:83], v[82:83], 1.0 op_sel_hi:[1,0]
	v_and_b32_e32 v105, 0xffff0000, v39
	v_rcp_f32_e32 v82, v82
	v_rcp_f32_e32 v83, v83
	v_pk_fma_f32 v[78:79], v[78:79], v[104:105], v[94:95]
	v_lshlrev_b32_e32 v94, 16, v42
	v_and_b32_e32 v95, 0xffff0000, v42
	v_pk_fma_f32 v[76:77], v[88:89], v[94:95], v[76:77]
	v_pk_mul_f32 v[80:81], v[80:81], v[82:83]
	v_pk_mul_f32 v[82:83], v[76:77], s[4:5] op_sel_hi:[1,0]
	v_lshlrev_b32_e32 v96, 16, v43
	v_exp_f32_e32 v82, v82
	v_exp_f32_e32 v83, v83
	v_and_b32_e32 v97, 0xffff0000, v43
	v_pk_fma_f32 v[78:79], v[90:91], v[96:97], v[78:79]
	v_pk_add_f32 v[82:83], v[82:83], 1.0 op_sel_hi:[1,0]
	s_nop 0
	v_rcp_f32_e32 v82, v82
	v_rcp_f32_e32 v83, v83
	s_nop 0
	v_pk_mul_f32 v[82:83], v[76:77], v[82:83]
	v_pk_mul_f32 v[76:77], v[78:79], s[4:5] op_sel_hi:[1,0]
	s_nop 0
	v_exp_f32_e32 v76, v76
	v_exp_f32_e32 v77, v77
	s_nop 0
	v_pk_add_f32 v[76:77], v[76:77], 1.0 op_sel_hi:[1,0]
	s_nop 0
	v_rcp_f32_e32 v76, v76
	v_rcp_f32_e32 v77, v77
	s_nop 0
	v_pk_mul_f32 v[84:85], v[78:79], v[76:77]
	v_cvt_pk_bf16_f32 v76, v2, v3
	v_cvt_pk_bf16_f32 v2, v44, v45
	v_cvt_pk_bf16_f32 v3, v46, v47
	v_cvt_pk_bf16_f32 v77, v80, v81
	v_cvt_pk_bf16_f32 v78, v82, v83
	s_nop 0
	v_cvt_pk_bf16_f32 v79, v84, v85
	ds_write_b128 v134, v[76:79]
	ds_write_b64 v216, v[2:3] offset:55296
	v_cvt_pk_bf16_f32 v2, v48, v49
	v_cvt_pk_bf16_f32 v3, v50, v51
	ds_write_b64 v217, v[2:3] offset:55296
	v_cvt_pk_bf16_f32 v2, v52, v53
	v_cvt_pk_bf16_f32 v3, v54, v55
	ds_write_b64 v218, v[2:3] offset:55296
	v_cvt_pk_bf16_f32 v2, v56, v57
	v_cvt_pk_bf16_f32 v3, v58, v59
	ds_write_b64 v219, v[2:3] offset:55296
	s_and_saveexec_b64 s[6:7], s[0:1]
	ds_write_b32 v133, v1
	s_or_b64 exec, exec, s[6:7]
	s_cmp_lt_i32 s46, 0
	s_waitcnt lgkmcnt(0)
	s_barrier
	s_cbranch_scc1 .LBB0_810
	s_lshr_b32 s4, s46, 2
	s_add_i32 s5, s4, 0xffffff7e
	s_cmpk_lt_u32 s46, 0x208
	s_cselect_b32 s6, s4, s5
	s_and_b32 s41, s46, 3
	s_lshl_b32 s53, s6, 7
	s_cmpk_gt_u32 s46, 0x207
	s_cselect_b64 s[46:47], -1, 0
	s_and_b64 s[4:5], s[46:47], exec
	s_cselect_b32 s52, 0x4100, 0
	s_and_b64 vcc, exec, s[48:49]
	s_add_i32 s7, s53, s52
	s_cbranch_vccnz .LBB0_794
	v_readlane_b32 s4, v238, 50
	s_or_b32 s4, s4, s41
	s_ashr_i32 s5, s4, 31
	s_mov_b32 s44, s21
	s_mov_b32 s58, s24
	v_readlane_b32 s16, v242, 10
	s_lshl_b64 s[4:5], s[4:5], 2
	v_readlane_b32 s24, v242, 18
	v_readlane_b32 s25, v242, 19
	s_add_u32 s4, s24, s4
	s_addc_u32 s5, s25, s5
	global_load_dword v2, v0, s[4:5]
	v_readlane_b32 s4, v238, 52
	s_add_u32 s4, s4, s41
	v_readlane_b32 s5, v238, 54
	v_readlane_b32 s17, v242, 11
	s_addc_u32 s5, s5, 0
	s_lshl_b64 s[4:5], s[4:5], 2
	v_readlane_b32 s16, v239, 23
	v_readlane_b32 s20, v242, 14
	s_add_u32 s4, s24, s4
	v_readlane_b32 s17, v239, 24
	s_addc_u32 s5, s25, s5
	v_or_b32_e32 v1, s7, v202
	v_mov_b64_e32 v[6:7], s[16:17]
	s_movk_i32 s20, 0x1400
	v_readlane_b32 s18, v242, 12
	global_load_dword v4, v0, s[4:5] offset:16
	v_mad_u64_u32 v[8:9], s[4:5], v1, s20, v[6:7]
	v_or_b32_e32 v1, s7, v204
	v_mad_u64_u32 v[6:7], s[4:5], v1, s20, v[6:7]
	v_readlane_b32 s18, v238, 51
	s_or_b32 s4, s18, s41
	s_ashr_i32 s5, s4, 31
	s_mov_b32 s24, s58
	s_lshl_b64 s[58:59], s[4:5], 1
	v_lshl_add_u64 v[10:11], v[8:9], 0, s[58:59]
	v_lshl_add_u64 v[12:13], v[6:7], 0, s[58:59]
	global_load_ushort v1, v[10:11], off offset:3072
	global_load_ushort v3, v[12:13], off offset:3072
	s_add_u32 s58, s18, s41
	v_readlane_b32 s5, v238, 53
	s_addc_u32 s59, s5, 0
	s_lshl_b64 s[58:59], s[58:59], 1
	v_lshl_add_u64 v[6:7], v[6:7], 0, s[58:59]
	v_readlane_b32 s19, v242, 13
	v_readlane_b32 s18, v242, 41
	v_readlane_b32 s19, v242, 42
	v_readlane_b32 s21, v242, 15
	s_mov_b32 s21, s44
	v_readlane_b32 s22, v242, 16
	v_readlane_b32 s23, v242, 17
	v_readlane_b32 s26, v242, 20
	v_readlane_b32 s27, v242, 21
	v_readlane_b32 s28, v242, 22
	v_readlane_b32 s29, v242, 23
	v_readlane_b32 s30, v242, 24
	v_readlane_b32 s31, v242, 25
	s_waitcnt vmcnt(1)
	v_lshlrev_b32_e32 v10, 16, v1
	s_waitcnt vmcnt(0)
	v_lshlrev_b32_e32 v11, 16, v3
	v_pk_add_f32 v[124:125], v[2:3], v[10:11] op_sel_hi:[0,1]
	v_lshl_add_u64 v[2:3], v[8:9], 0, s[58:59]
	s_and_b64 s[58:59], s[46:47], exec
	s_cselect_b32 s5, 4, 0
	s_or_b32 s4, s4, s5
	s_mulk_i32 s4, 0x82
	s_add_i32 s4, s4, s6
	s_ashr_i32 s5, s4, 31
	s_lshl_b64 s[4:5], s[4:5], 2
	global_load_ushort v1, v[2:3], off offset:3080
	s_nop 0
	global_load_ushort v2, v[6:7], off offset:3080
	s_add_u32 s4, s18, s4
	s_addc_u32 s5, s19, s5
	global_load_dword v157, v0, s[4:5]
	s_waitcnt vmcnt(1)
	v_lshlrev_b32_e32 v3, 16, v2
	v_lshlrev_b32_e32 v2, 16, v1
	v_pk_add_f32 v[128:129], v[4:5], v[2:3] op_sel_hi:[0,1]
	s_branch .LBB0_795
